# speedup vs baseline: 1.0054x; 1.0054x over previous
; #define LAS __attribute__((address_space(3)))
; __device__ __forceinline__ void rw_scan4(const int tid, LAS float* lds, const float* RW, int task, int ntasks, int mode, const float* SIN, float* PQ, float* Y) {
;     const int slot = tid >> 7, sl = tid & 127, kp = sl & 7, rg = sl >> 3;
;     const bool active = task < ntasks;
;     int head = 0, c = 0, kind = 2;
;     if (active) { if (mode == 0) { kind = task & 1; head = (task >> 1) & 7; c = task >> 4; } else { head = task & 7; c = task >> 3; } }
;     const int t0 = c * CHL;
;     f32x2 s[4][4];
;     if (kind == 2 && active) {
;         const float* ip = SIN + (size_t)(head * NCH + c) * 4096 + (rg * 4) * 64 + kp * 8;
; #pragma unroll
;         for (int j = 0; j < 4; ++j) { const f32x4 i0 = *(const f32x4*)(ip + j * 64), i1 = *(const f32x4*)(ip + j * 64 + 4);
;             s[j][0] = (f32x2){i0.x, i0.y}; s[j][1] = (f32x2){i0.z, i0.w}; s[j][2] = (f32x2){i1.x, i1.y}; s[j][3] = (f32x2){i1.z, i1.w}; }
;     } else {
; #pragma unroll
;         for (int j = 0; j < 4; ++j)
; #pragma unroll
;             for (int i = 0; i < 4; ++i) { const int kk = kp * 8 + 2 * i, rr = rg * 4 + j; s[j][i] = (f32x2){(kind == 1 && kk == rr) ? 1.f : 0.f, (kind == 1 && kk + 1 == rr) ? 1.f : 0.f}; }
;     }
;     LAS float* sb = lds + slot * (2 * 6 * TB * 64);
;     const int srow = sl >> 4, sc4 = sl & 15;
;     const float* gsrc = RW + (size_t)(t0 + srow) * GW + head * 64 + sc4 * 4;
;     f32x4 st[6];
.Lp8_main:
	s_setprio 2
	s_waitcnt vmcnt(5)
	v_ashrrev_i32_e32 v0, 7, v148
	v_mul_lo_u32 v1, v0, s45
	s_waitcnt vmcnt(4)
	v_bfe_u32 v6, v148, 3, 4
	s_movk_i32 s4, 0x6000
	v_add_u32_e32 v76, s44, v1
	v_and_b32_e32 v1, 7, v148
	v_mul_lo_u32 v7, v0, s4
	v_lshlrev_b32_e32 v0, 2, v148
	v_lshlrev_b32_e32 v4, 10, v6
	v_mov_b32_e32 v5, v144
	v_bfe_u32 v77, v148, 4, 3
	v_and_b32_e32 v0, 60, v0
	v_lshlrev_b32_e32 v2, 5, v1
	s_waitcnt lgkmcnt(0)
	v_lshl_add_u64 v[4:5], s[18:19], 0, v[4:5]
	v_mov_b32_e32 v3, v144
	s_waitcnt vmcnt(3)
	v_add_u32_e32 v8, 0, v7
	v_lshlrev_b32_e32 v9, 2, v0
	v_cmp_eq_u32_e64 s[38:39], 0, v1
	v_lshl_add_u64 v[4:5], v[4:5], 0, v[2:3]
	s_mov_b64 s[4:5], 0x29300000
	v_lshlrev_b32_e32 v1, 8, v77
	v_lshl_add_u64 v[56:57], v[4:5], 0, s[4:5]
	v_add3_u32 v78, v8, v9, v1
	v_lshl_or_b32 v1, v6, 4, v7
	v_readlane_b32 s4, v254, 15
	s_add_u32 s0, s18, 0x16200000
	s_addc_u32 s1, s19, 0
	v_add_u32_e32 v79, s4, v1
	v_or_b32_e32 v1, v7, v2
	v_add_u32_e32 v80, 0, v1
	v_lshlrev_b32_e32 v1, 1, v148
	v_and_b32_e32 v2, 0xf0, v1
	s_mov_b32 s14, 0
	s_lshl_b32 s15, s45, 2
	v_lshl_add_u64 v[58:59], s[18:19], 0, v[2:3]
	v_lshlrev_b32_e32 v60, 2, v0
	v_mov_b32_e32 v81, v76
	s_branch .LBB0_69

; __global__ void __launch_bounds__(NTHR, 2) hymba_fwd(Args args) {
;     ...
;             for (int tb = 0; tb < NCH * 8; tb += 4 * G) rw_scan4(tid, ldsf, WSP(float, WS_RW), tb + (tid >> 7) * G + bid, NCH * 8, 2, WSP(float, WS_SIN), nullptr, WSP(float, WS_Y));
.LBB0_90:
	s_setprio 0
	s_mov_b64 s[0:1], 0
